# FFN down epilogues (P2/P10): residual-tile loads of all 8 row groups issued up front with counted vmcnt waits
# speedup vs baseline: 1.0081x; 1.0008x over previous
.LBB0_196:
	v_mov_b32_e32 v80, v192
	s_lshl_b32 s41, s73, 8
	s_lshl_b32 s40, s72, 8
	v_ashrrev_i32_e32 v142, 2, v80
	v_and_b32_e32 v142, 0xffffffc0, v142
	v_and_or_b32 v143, v80, 15, s41
	v_add_u32_e32 v142, v143, v142
	v_ashrrev_i32_e32 v143, 31, v142
	v_bfe_u32 v147, v80, 4, 2
	v_lshrrev_b32_e32 v80, 1, v80
	v_lshlrev_b64 v[148:149], 11, v[142:143]
	s_ashr_i32 s41, s40, 31
	v_and_b32_e32 v80, 0x60, v80
	v_lshl_add_u64 v[148:149], s[38:39], 0, v[148:149]
	v_lshl_add_u64 v[148:149], s[40:41], 1, v[148:149]
	v_lshlrev_b32_e32 v80, 1, v80
	v_lshl_add_u64 v[148:149], v[148:149], 0, v[80:81]
	v_lshlrev_b32_e32 v150, 4, v147
	v_mov_b32_e32 v151, v81
	v_lshl_add_u64 v[164:165], v[148:149], 0, v[150:151]
	global_load_dwordx4 v[148:151], v[164:165], off
	global_load_dwordx4 v[160:163], v[164:165], off offset:256
	v_mov_b32_e32 v248, v164
	v_mov_b32_e32 v249, v165
	v_add_co_u32_e32 v248, vcc, 0x8000, v248
	s_nop 1
	v_addc_co_u32_e32 v249, vcc, 0, v249, vcc
	global_load_dwordx4 v[176:179], v[248:249], off
	global_load_dwordx4 v[180:183], v[248:249], off offset:256
	v_add_co_u32_e32 v248, vcc, 0x8000, v248
	s_nop 1
	v_addc_co_u32_e32 v249, vcc, 0, v249, vcc
	global_load_dwordx4 v[184:187], v[248:249], off
	global_load_dwordx4 v[188:191], v[248:249], off offset:256
	v_add_co_u32_e32 v248, vcc, 0x8000, v248
	s_nop 1
	v_addc_co_u32_e32 v249, vcc, 0, v249, vcc
	global_load_dwordx4 v[204:207], v[248:249], off
	global_load_dwordx4 v[208:211], v[248:249], off offset:256
	v_add_co_u32_e32 v248, vcc, 0x28000, v248
	s_nop 1
	v_addc_co_u32_e32 v249, vcc, 0, v249, vcc
	global_load_dwordx4 v[212:215], v[248:249], off
	global_load_dwordx4 v[216:219], v[248:249], off offset:256
	v_add_co_u32_e32 v248, vcc, 0x8000, v248
	s_nop 1
	v_addc_co_u32_e32 v249, vcc, 0, v249, vcc
	global_load_dwordx4 v[220:223], v[248:249], off
	global_load_dwordx4 v[224:227], v[248:249], off offset:256
	v_add_co_u32_e32 v248, vcc, 0x8000, v248
	s_nop 1
	v_addc_co_u32_e32 v249, vcc, 0, v249, vcc
	global_load_dwordx4 v[228:231], v[248:249], off
	global_load_dwordx4 v[232:235], v[248:249], off offset:256
	v_add_co_u32_e32 v248, vcc, 0x8000, v248
	s_nop 1
	v_addc_co_u32_e32 v249, vcc, 0, v249, vcc
	global_load_dwordx4 v[236:239], v[248:249], off
	global_load_dwordx4 v[240:243], v[248:249], off offset:256
	v_xor_b32_e32 v146, 16, v195
	v_cmp_lt_i32_e32 vcc, v196, v197
	s_waitcnt vmcnt(14)
	v_lshlrev_b32_e32 v166, 16, v148
	v_and_b32_e32 v167, 0xffff0000, v148
	v_lshlrev_b32_e32 v170, 16, v160
	v_and_b32_e32 v171, 0xffff0000, v160
	v_lshlrev_b32_e32 v168, 16, v150
	v_and_b32_e32 v169, 0xffff0000, v150
	v_lshlrev_b32_e32 v150, 16, v151
	v_and_b32_e32 v151, 0xffff0000, v151
	v_lshlrev_b32_e32 v172, 16, v162
	v_and_b32_e32 v173, 0xffff0000, v162
	v_lshlrev_b32_e32 v162, 16, v163
	v_and_b32_e32 v163, 0xffff0000, v163
	v_pk_fma_f32 v[126:127], v[126:127], 0.5, v[166:167] op_sel_hi:[1,0,1]
	v_pk_fma_f32 v[118:119], v[118:119], 0.5, v[170:171] op_sel_hi:[1,0,1]
	v_lshlrev_b32_e32 v148, 16, v149
	v_and_b32_e32 v149, 0xffff0000, v149
	v_lshlrev_b32_e32 v160, 16, v161
	v_and_b32_e32 v161, 0xffff0000, v161
	v_pk_fma_f32 v[124:125], v[124:125], 0.5, v[150:151] op_sel_hi:[1,0,1]
	v_pk_fma_f32 v[150:151], v[116:117], 0.5, v[162:163] op_sel_hi:[1,0,1]
	v_mul_f32_e32 v116, v127, v127
	v_mul_f32_e32 v117, v119, v119
	v_pk_fma_f32 v[128:129], v[128:129], 0.5, v[148:149] op_sel_hi:[1,0,1]
	v_pk_fma_f32 v[148:149], v[120:121], 0.5, v[160:161] op_sel_hi:[1,0,1]
	v_fmac_f32_e32 v116, v126, v126
	v_fmac_f32_e32 v117, v118, v118
	v_fmac_f32_e32 v116, v128, v128
	v_fmac_f32_e32 v117, v148, v148
	v_pk_fma_f32 v[122:123], v[122:123], 0.5, v[168:169] op_sel_hi:[1,0,1]
	v_pk_fma_f32 v[160:161], v[114:115], 0.5, v[172:173] op_sel_hi:[1,0,1]
	v_fmac_f32_e32 v116, v129, v129
	v_fmac_f32_e32 v117, v149, v149
	v_fmac_f32_e32 v116, v122, v122
	v_fmac_f32_e32 v117, v160, v160
	v_fmac_f32_e32 v116, v123, v123
	v_fmac_f32_e32 v117, v161, v161
	v_cndmask_b32_e32 v174, v195, v196, vcc
	v_cmp_lt_i32_e32 vcc, v146, v197
	v_fmac_f32_e32 v116, v124, v124
	v_fmac_f32_e32 v117, v150, v150
	v_cndmask_b32_e32 v146, v195, v146, vcc
	v_fmac_f32_e32 v116, v125, v125
	v_fmac_f32_e32 v117, v151, v151
	v_lshlrev_b32_e32 v146, 2, v146
	v_add_f32_e32 v121, v116, v117
	v_cvt_pk_bf16_f32 v114, v126, v127
	ds_bpermute_b32 v126, v146, v121
	v_cvt_pk_bf16_f32 v115, v128, v129
	v_cvt_pk_bf16_f32 v116, v122, v123
	v_cvt_pk_bf16_f32 v117, v124, v125
	global_store_dwordx4 v[164:165], v[114:117], off
	v_cvt_pk_bf16_f32 v120, v118, v119
	v_lshlrev_b32_e32 v118, 2, v174
	v_cmp_eq_u32_e32 vcc, 0, v147
	s_waitcnt lgkmcnt(0)
	v_add_f32_e32 v114, v121, v126
	ds_bpermute_b32 v115, v118, v114
	v_cvt_pk_bf16_f32 v121, v148, v149
	v_cvt_pk_bf16_f32 v122, v160, v161
	v_cvt_pk_bf16_f32 v123, v150, v151
	global_store_dwordx4 v[164:165], v[120:123], off offset:256
	s_and_saveexec_b64 s[44:45], vcc
	s_cbranch_execz .LBB0_198
	v_readlane_b32 s54, v253, 14
	v_readlane_b32 s55, v253, 15
	s_waitcnt lgkmcnt(0)
	v_add_f32_e32 v114, v114, v115
	v_lshl_add_u64 v[116:117], v[142:143], 2, s[54:55]
	global_atomic_add_f32 v[116:117], v114, off
.LBB0_198:
	s_or_b64 exec, exec, s[44:45]
	v_or_b32_e32 v116, 16, v142
	v_ashrrev_i32_e32 v117, 31, v116
	s_waitcnt lgkmcnt(0)
	v_lshlrev_b64 v[114:115], 11, v[116:117]
	v_lshl_add_u64 v[114:115], s[38:39], 0, v[114:115]
	v_lshlrev_b32_e32 v119, 3, v147
	v_lshl_add_u64 v[114:115], s[40:41], 1, v[114:115]
	v_lshl_add_u64 v[120:121], v[114:115], 0, v[80:81]
	v_lshlrev_b32_e32 v114, 1, v119
	v_mov_b32_e32 v115, v81
	v_lshl_add_u64 v[128:129], v[120:121], 0, v[114:115]
	s_waitcnt vmcnt(14)
	v_lshlrev_b32_e32 v148, 16, v176
	v_and_b32_e32 v149, 0xffff0000, v176
	v_pk_fma_f32 v[110:111], v[110:111], 0.5, v[148:149] op_sel_hi:[1,0,1]
	v_lshlrev_b32_e32 v120, 16, v177
	v_and_b32_e32 v121, 0xffff0000, v177
	v_lshlrev_b32_e32 v150, 16, v178
	v_and_b32_e32 v151, 0xffff0000, v178
	v_lshlrev_b32_e32 v122, 16, v179
	v_and_b32_e32 v123, 0xffff0000, v179
	v_mul_f32_e32 v119, v111, v111
	v_pk_fma_f32 v[112:113], v[112:113], 0.5, v[120:121] op_sel_hi:[1,0,1]
	v_pk_fma_f32 v[120:121], v[108:109], 0.5, v[122:123] op_sel_hi:[1,0,1]
	v_pk_fma_f32 v[122:123], v[106:107], 0.5, v[150:151] op_sel_hi:[1,0,1]
	v_cvt_pk_bf16_f32 v106, v110, v111
	v_cvt_pk_bf16_f32 v107, v112, v113
	v_fmac_f32_e32 v119, v110, v110
	v_cvt_pk_bf16_f32 v108, v122, v123
	v_cvt_pk_bf16_f32 v109, v120, v121
	global_store_dwordx4 v[128:129], v[106:109], off
	v_fmac_f32_e32 v119, v112, v112
	v_lshlrev_b32_e32 v110, 16, v182
	v_lshlrev_b32_e32 v106, 16, v180
	v_and_b32_e32 v107, 0xffff0000, v180
	v_lshlrev_b32_e32 v108, 16, v181
	v_and_b32_e32 v109, 0xffff0000, v181
	v_and_b32_e32 v111, 0xffff0000, v182
	v_fmac_f32_e32 v119, v113, v113
	v_lshlrev_b32_e32 v112, 16, v183
	v_and_b32_e32 v113, 0xffff0000, v183
	v_pk_fma_f32 v[104:105], v[104:105], 0.5, v[108:109] op_sel_hi:[1,0,1]
	v_pk_fma_f32 v[102:103], v[102:103], 0.5, v[106:107] op_sel_hi:[1,0,1]
	v_pk_fma_f32 v[108:109], v[98:99], 0.5, v[110:111] op_sel_hi:[1,0,1]
	v_cvt_pk_bf16_f32 v98, v102, v103
	v_pk_fma_f32 v[106:107], v[100:101], 0.5, v[112:113] op_sel_hi:[1,0,1]
	v_cvt_pk_bf16_f32 v99, v104, v105
	v_cvt_pk_bf16_f32 v100, v108, v109
	v_fmac_f32_e32 v119, v122, v122
	v_cvt_pk_bf16_f32 v101, v106, v107
	global_store_dwordx4 v[128:129], v[98:101], off offset:256
	v_fmac_f32_e32 v119, v123, v123
	v_fmac_f32_e32 v119, v120, v120
	v_mul_f32_e32 v98, v103, v103
	v_fmac_f32_e32 v98, v102, v102
	v_fmac_f32_e32 v98, v104, v104
	v_fmac_f32_e32 v98, v105, v105
	v_fmac_f32_e32 v98, v108, v108
	v_fmac_f32_e32 v98, v109, v109
	v_fmac_f32_e32 v98, v106, v106
	v_fmac_f32_e32 v119, v121, v121
	v_fmac_f32_e32 v98, v107, v107
	v_add_f32_e32 v98, v119, v98
	ds_bpermute_b32 v99, v146, v98
	s_waitcnt lgkmcnt(0)
	v_add_f32_e32 v98, v98, v99
	ds_bpermute_b32 v99, v118, v98
	s_and_saveexec_b64 s[44:45], vcc
	s_cbranch_execz .LBB0_200
	v_readlane_b32 s54, v253, 14
	v_readlane_b32 s55, v253, 15
	s_waitcnt lgkmcnt(0)
	v_add_f32_e32 v98, v98, v99
	v_lshl_add_u64 v[100:101], v[116:117], 2, s[54:55]
	global_atomic_add_f32 v[100:101], v98, off
.LBB0_200:
	s_or_b64 exec, exec, s[44:45]
	v_or_b32_e32 v98, 32, v142
	s_waitcnt lgkmcnt(0)
	v_ashrrev_i32_e32 v99, 31, v98
	v_lshlrev_b64 v[100:101], 11, v[98:99]
	v_lshl_add_u64 v[100:101], s[38:39], 0, v[100:101]
	v_lshl_add_u64 v[100:101], s[40:41], 1, v[100:101]
	v_lshl_add_u64 v[100:101], v[100:101], 0, v[80:81]
	v_lshl_add_u64 v[108:109], v[100:101], 0, v[114:115]
	s_waitcnt vmcnt(14)
	v_lshlrev_b32_e32 v110, 16, v184
	v_and_b32_e32 v111, 0xffff0000, v184
	v_pk_fma_f32 v[94:95], v[94:95], 0.5, v[110:111] op_sel_hi:[1,0,1]
	v_lshlrev_b32_e32 v100, 16, v185
	v_and_b32_e32 v101, 0xffff0000, v185
	v_lshlrev_b32_e32 v112, 16, v186
	v_and_b32_e32 v113, 0xffff0000, v186
	v_lshlrev_b32_e32 v102, 16, v187
	v_and_b32_e32 v103, 0xffff0000, v187
	v_mul_f32_e32 v110, v95, v95
	v_pk_fma_f32 v[96:97], v[96:97], 0.5, v[100:101] op_sel_hi:[1,0,1]
	v_pk_fma_f32 v[100:101], v[92:93], 0.5, v[102:103] op_sel_hi:[1,0,1]
	v_pk_fma_f32 v[102:103], v[90:91], 0.5, v[112:113] op_sel_hi:[1,0,1]
	v_cvt_pk_bf16_f32 v90, v94, v95
	v_cvt_pk_bf16_f32 v91, v96, v97
	v_fmac_f32_e32 v110, v94, v94
	v_cvt_pk_bf16_f32 v92, v102, v103
	v_cvt_pk_bf16_f32 v93, v100, v101
	global_store_dwordx4 v[108:109], v[90:93], off
	v_fmac_f32_e32 v110, v96, v96
	v_lshlrev_b32_e32 v94, 16, v190
	v_lshlrev_b32_e32 v90, 16, v188
	v_and_b32_e32 v91, 0xffff0000, v188
	v_lshlrev_b32_e32 v92, 16, v189
	v_and_b32_e32 v93, 0xffff0000, v189
	v_and_b32_e32 v95, 0xffff0000, v190
	v_fmac_f32_e32 v110, v97, v97
	v_lshlrev_b32_e32 v96, 16, v191
	v_and_b32_e32 v97, 0xffff0000, v191
	v_pk_fma_f32 v[88:89], v[88:89], 0.5, v[92:93] op_sel_hi:[1,0,1]
	v_pk_fma_f32 v[86:87], v[86:87], 0.5, v[90:91] op_sel_hi:[1,0,1]
	v_pk_fma_f32 v[92:93], v[82:83], 0.5, v[94:95] op_sel_hi:[1,0,1]
	v_cvt_pk_bf16_f32 v82, v86, v87
	v_pk_fma_f32 v[90:91], v[84:85], 0.5, v[96:97] op_sel_hi:[1,0,1]
	v_cvt_pk_bf16_f32 v83, v88, v89
	v_cvt_pk_bf16_f32 v84, v92, v93
	v_fmac_f32_e32 v110, v102, v102
	v_cvt_pk_bf16_f32 v85, v90, v91
	global_store_dwordx4 v[108:109], v[82:85], off offset:256
	v_fmac_f32_e32 v110, v103, v103
	v_fmac_f32_e32 v110, v100, v100
	v_mul_f32_e32 v82, v87, v87
	v_fmac_f32_e32 v82, v86, v86
	v_fmac_f32_e32 v82, v88, v88
	v_fmac_f32_e32 v82, v89, v89
	v_fmac_f32_e32 v82, v92, v92
	v_fmac_f32_e32 v82, v93, v93
	v_fmac_f32_e32 v82, v90, v90
	v_fmac_f32_e32 v110, v101, v101
	v_fmac_f32_e32 v82, v91, v91
	v_add_f32_e32 v82, v110, v82
	ds_bpermute_b32 v83, v146, v82
	s_waitcnt lgkmcnt(0)
	v_add_f32_e32 v82, v82, v83
	ds_bpermute_b32 v83, v118, v82
	s_and_saveexec_b64 s[44:45], vcc
	s_cbranch_execz .LBB0_202
	v_readlane_b32 s54, v253, 14
	v_readlane_b32 s55, v253, 15
	s_waitcnt lgkmcnt(0)
	v_add_f32_e32 v82, v82, v83
	v_lshl_add_u64 v[84:85], v[98:99], 2, s[54:55]
	global_atomic_add_f32 v[84:85], v82, off
.LBB0_202:
	s_or_b64 exec, exec, s[44:45]
	v_or_b32_e32 v82, 48, v142
	s_waitcnt lgkmcnt(0)
	v_ashrrev_i32_e32 v83, 31, v82
	v_lshlrev_b64 v[84:85], 11, v[82:83]
	v_lshl_add_u64 v[84:85], s[38:39], 0, v[84:85]
	v_lshl_add_u64 v[84:85], s[40:41], 1, v[84:85]
	v_lshl_add_u64 v[84:85], v[84:85], 0, v[80:81]
	v_mov_b32_e32 v115, v81
	v_lshl_add_u64 v[92:93], v[84:85], 0, v[114:115]
	s_waitcnt vmcnt(14)
	v_lshlrev_b32_e32 v94, 16, v204
	v_and_b32_e32 v95, 0xffff0000, v204
	v_pk_fma_f32 v[76:77], v[76:77], 0.5, v[94:95] op_sel_hi:[1,0,1]
	v_lshlrev_b32_e32 v84, 16, v205
	v_and_b32_e32 v85, 0xffff0000, v205
	v_lshlrev_b32_e32 v96, 16, v206
	v_and_b32_e32 v97, 0xffff0000, v206
	v_lshlrev_b32_e32 v86, 16, v207
	v_and_b32_e32 v87, 0xffff0000, v207
	v_mul_f32_e32 v94, v77, v77
	v_pk_fma_f32 v[78:79], v[78:79], 0.5, v[84:85] op_sel_hi:[1,0,1]
	v_pk_fma_f32 v[84:85], v[74:75], 0.5, v[86:87] op_sel_hi:[1,0,1]
	v_pk_fma_f32 v[86:87], v[72:73], 0.5, v[96:97] op_sel_hi:[1,0,1]
	v_cvt_pk_bf16_f32 v72, v76, v77
	v_cvt_pk_bf16_f32 v73, v78, v79
	v_fmac_f32_e32 v94, v76, v76
	v_cvt_pk_bf16_f32 v74, v86, v87
	v_cvt_pk_bf16_f32 v75, v84, v85
	global_store_dwordx4 v[92:93], v[72:75], off
	v_fmac_f32_e32 v94, v78, v78
	v_lshlrev_b32_e32 v76, 16, v210
	v_lshlrev_b32_e32 v72, 16, v208
	v_and_b32_e32 v73, 0xffff0000, v208
	v_lshlrev_b32_e32 v74, 16, v209
	v_and_b32_e32 v75, 0xffff0000, v209
	v_and_b32_e32 v77, 0xffff0000, v210
	v_fmac_f32_e32 v94, v79, v79
	v_lshlrev_b32_e32 v78, 16, v211
	v_and_b32_e32 v79, 0xffff0000, v211
	v_pk_fma_f32 v[70:71], v[70:71], 0.5, v[74:75] op_sel_hi:[1,0,1]
	v_pk_fma_f32 v[68:69], v[68:69], 0.5, v[72:73] op_sel_hi:[1,0,1]
	v_pk_fma_f32 v[74:75], v[64:65], 0.5, v[76:77] op_sel_hi:[1,0,1]
	v_cvt_pk_bf16_f32 v64, v68, v69
	v_pk_fma_f32 v[72:73], v[66:67], 0.5, v[78:79] op_sel_hi:[1,0,1]
	v_cvt_pk_bf16_f32 v65, v70, v71
	v_cvt_pk_bf16_f32 v66, v74, v75
	v_fmac_f32_e32 v94, v86, v86
	v_cvt_pk_bf16_f32 v67, v72, v73
	global_store_dwordx4 v[92:93], v[64:67], off offset:256
	v_fmac_f32_e32 v94, v87, v87
	v_fmac_f32_e32 v94, v84, v84
	v_mul_f32_e32 v64, v69, v69
	v_fmac_f32_e32 v64, v68, v68
	v_fmac_f32_e32 v64, v70, v70
	v_fmac_f32_e32 v64, v71, v71
	v_fmac_f32_e32 v64, v74, v74
	v_fmac_f32_e32 v64, v75, v75
	v_fmac_f32_e32 v64, v72, v72
	v_fmac_f32_e32 v94, v85, v85
	v_fmac_f32_e32 v64, v73, v73
	v_add_f32_e32 v64, v94, v64
	ds_bpermute_b32 v65, v146, v64
	s_waitcnt lgkmcnt(0)
	v_add_f32_e32 v64, v64, v65
	ds_bpermute_b32 v65, v118, v64
	s_and_saveexec_b64 s[44:45], vcc
	s_cbranch_execz .LBB0_204
	v_readlane_b32 s54, v253, 14
	v_readlane_b32 s55, v253, 15
	s_waitcnt lgkmcnt(0)
	v_add_f32_e32 v64, v64, v65
	v_lshl_add_u64 v[66:67], v[82:83], 2, s[54:55]
	global_atomic_add_f32 v[66:67], v64, off
.LBB0_204:
	s_or_b64 exec, exec, s[44:45]
	v_add_u32_e32 v64, 0x80, v142
	s_waitcnt lgkmcnt(0)
	v_ashrrev_i32_e32 v65, 31, v64
	v_lshlrev_b64 v[66:67], 11, v[64:65]
	v_lshl_add_u64 v[66:67], s[38:39], 0, v[66:67]
	v_lshl_add_u64 v[66:67], s[40:41], 1, v[66:67]
	v_lshl_add_u64 v[66:67], v[66:67], 0, v[80:81]
	v_lshl_add_u64 v[74:75], v[66:67], 0, v[114:115]
	s_waitcnt vmcnt(14)
	v_lshlrev_b32_e32 v76, 16, v212
	v_and_b32_e32 v77, 0xffff0000, v212
	v_pk_fma_f32 v[60:61], v[60:61], 0.5, v[76:77] op_sel_hi:[1,0,1]
	v_lshlrev_b32_e32 v66, 16, v213
	v_and_b32_e32 v67, 0xffff0000, v213
	v_lshlrev_b32_e32 v78, 16, v214
	v_and_b32_e32 v79, 0xffff0000, v214
	v_lshlrev_b32_e32 v68, 16, v215
	v_and_b32_e32 v69, 0xffff0000, v215
	v_mul_f32_e32 v76, v61, v61
	v_pk_fma_f32 v[62:63], v[62:63], 0.5, v[66:67] op_sel_hi:[1,0,1]
	v_pk_fma_f32 v[66:67], v[58:59], 0.5, v[68:69] op_sel_hi:[1,0,1]
	v_pk_fma_f32 v[68:69], v[56:57], 0.5, v[78:79] op_sel_hi:[1,0,1]
	v_cvt_pk_bf16_f32 v56, v60, v61
	v_cvt_pk_bf16_f32 v57, v62, v63
	v_fmac_f32_e32 v76, v60, v60
	v_cvt_pk_bf16_f32 v58, v68, v69
	v_cvt_pk_bf16_f32 v59, v66, v67
	global_store_dwordx4 v[74:75], v[56:59], off
	v_fmac_f32_e32 v76, v62, v62
	v_lshlrev_b32_e32 v60, 16, v218
	v_lshlrev_b32_e32 v56, 16, v216
	v_and_b32_e32 v57, 0xffff0000, v216
	v_lshlrev_b32_e32 v58, 16, v217
	v_and_b32_e32 v59, 0xffff0000, v217
	v_and_b32_e32 v61, 0xffff0000, v218
	v_fmac_f32_e32 v76, v63, v63
	v_lshlrev_b32_e32 v62, 16, v219
	v_and_b32_e32 v63, 0xffff0000, v219
	v_pk_fma_f32 v[54:55], v[54:55], 0.5, v[58:59] op_sel_hi:[1,0,1]
	v_pk_fma_f32 v[52:53], v[52:53], 0.5, v[56:57] op_sel_hi:[1,0,1]
	v_pk_fma_f32 v[58:59], v[48:49], 0.5, v[60:61] op_sel_hi:[1,0,1]
	v_cvt_pk_bf16_f32 v48, v52, v53
	v_pk_fma_f32 v[56:57], v[50:51], 0.5, v[62:63] op_sel_hi:[1,0,1]
	v_cvt_pk_bf16_f32 v49, v54, v55
	v_cvt_pk_bf16_f32 v50, v58, v59
	v_fmac_f32_e32 v76, v68, v68
	v_cvt_pk_bf16_f32 v51, v56, v57
	global_store_dwordx4 v[74:75], v[48:51], off offset:256
	v_fmac_f32_e32 v76, v69, v69
	v_fmac_f32_e32 v76, v66, v66
	v_mul_f32_e32 v48, v53, v53
	v_fmac_f32_e32 v48, v52, v52
	v_fmac_f32_e32 v48, v54, v54
	v_fmac_f32_e32 v48, v55, v55
	v_fmac_f32_e32 v48, v58, v58
	v_fmac_f32_e32 v48, v59, v59
	v_fmac_f32_e32 v48, v56, v56
	v_fmac_f32_e32 v76, v67, v67
	v_fmac_f32_e32 v48, v57, v57
	v_add_f32_e32 v48, v76, v48
	ds_bpermute_b32 v49, v146, v48
	s_waitcnt lgkmcnt(0)
	v_add_f32_e32 v48, v48, v49
	ds_bpermute_b32 v49, v118, v48
	s_and_saveexec_b64 s[44:45], vcc
	s_cbranch_execz .LBB0_206
	v_readlane_b32 s54, v253, 14
	v_readlane_b32 s55, v253, 15
	s_waitcnt lgkmcnt(0)
	v_add_f32_e32 v48, v48, v49
	v_lshl_add_u64 v[50:51], v[64:65], 2, s[54:55]
	global_atomic_add_f32 v[50:51], v48, off
.LBB0_206:
	s_or_b64 exec, exec, s[44:45]
	v_add_u32_e32 v48, 0x90, v142
	s_waitcnt lgkmcnt(0)
	v_ashrrev_i32_e32 v49, 31, v48
	v_lshlrev_b64 v[50:51], 11, v[48:49]
	v_lshl_add_u64 v[50:51], s[38:39], 0, v[50:51]
	v_lshl_add_u64 v[50:51], s[40:41], 1, v[50:51]
	v_lshl_add_u64 v[50:51], v[50:51], 0, v[80:81]
	v_mov_b32_e32 v115, v81
	v_lshl_add_u64 v[58:59], v[50:51], 0, v[114:115]
	s_waitcnt vmcnt(14)
	v_lshlrev_b32_e32 v60, 16, v220
	v_and_b32_e32 v61, 0xffff0000, v220
	v_pk_fma_f32 v[44:45], v[44:45], 0.5, v[60:61] op_sel_hi:[1,0,1]
	v_lshlrev_b32_e32 v50, 16, v221
	v_and_b32_e32 v51, 0xffff0000, v221
	v_lshlrev_b32_e32 v62, 16, v222
	v_and_b32_e32 v63, 0xffff0000, v222
	v_lshlrev_b32_e32 v52, 16, v223
	v_and_b32_e32 v53, 0xffff0000, v223
	v_mul_f32_e32 v60, v45, v45
	v_pk_fma_f32 v[46:47], v[46:47], 0.5, v[50:51] op_sel_hi:[1,0,1]
	v_pk_fma_f32 v[50:51], v[42:43], 0.5, v[52:53] op_sel_hi:[1,0,1]
	v_pk_fma_f32 v[52:53], v[40:41], 0.5, v[62:63] op_sel_hi:[1,0,1]
	v_cvt_pk_bf16_f32 v40, v44, v45
	v_cvt_pk_bf16_f32 v41, v46, v47
	v_fmac_f32_e32 v60, v44, v44
	v_cvt_pk_bf16_f32 v42, v52, v53
	v_cvt_pk_bf16_f32 v43, v50, v51
	global_store_dwordx4 v[58:59], v[40:43], off
	v_fmac_f32_e32 v60, v46, v46
	v_lshlrev_b32_e32 v44, 16, v226
	v_lshlrev_b32_e32 v40, 16, v224
	v_and_b32_e32 v41, 0xffff0000, v224
	v_lshlrev_b32_e32 v42, 16, v225
	v_and_b32_e32 v43, 0xffff0000, v225
	v_and_b32_e32 v45, 0xffff0000, v226
	v_fmac_f32_e32 v60, v47, v47
	v_lshlrev_b32_e32 v46, 16, v227
	v_and_b32_e32 v47, 0xffff0000, v227
	v_pk_fma_f32 v[38:39], v[38:39], 0.5, v[42:43] op_sel_hi:[1,0,1]
	v_pk_fma_f32 v[36:37], v[36:37], 0.5, v[40:41] op_sel_hi:[1,0,1]
	v_pk_fma_f32 v[42:43], v[32:33], 0.5, v[44:45] op_sel_hi:[1,0,1]
	v_cvt_pk_bf16_f32 v32, v36, v37
	v_pk_fma_f32 v[40:41], v[34:35], 0.5, v[46:47] op_sel_hi:[1,0,1]
	v_cvt_pk_bf16_f32 v33, v38, v39
	v_cvt_pk_bf16_f32 v34, v42, v43
	v_fmac_f32_e32 v60, v52, v52
	v_cvt_pk_bf16_f32 v35, v40, v41
	global_store_dwordx4 v[58:59], v[32:35], off offset:256
	v_fmac_f32_e32 v60, v53, v53
	v_fmac_f32_e32 v60, v50, v50
	v_mul_f32_e32 v32, v37, v37
	v_fmac_f32_e32 v32, v36, v36
	v_fmac_f32_e32 v32, v38, v38
	v_fmac_f32_e32 v32, v39, v39
	v_fmac_f32_e32 v32, v42, v42
	v_fmac_f32_e32 v32, v43, v43
	v_fmac_f32_e32 v32, v40, v40
	v_fmac_f32_e32 v60, v51, v51
	v_fmac_f32_e32 v32, v41, v41
	v_add_f32_e32 v32, v60, v32
	ds_bpermute_b32 v33, v146, v32
	s_waitcnt lgkmcnt(0)
	v_add_f32_e32 v32, v32, v33
	ds_bpermute_b32 v33, v118, v32
	s_and_saveexec_b64 s[44:45], vcc
	s_cbranch_execz .LBB0_208
	v_readlane_b32 s54, v253, 14
	v_readlane_b32 s55, v253, 15
	s_waitcnt lgkmcnt(0)
	v_add_f32_e32 v32, v32, v33
	v_lshl_add_u64 v[34:35], v[48:49], 2, s[54:55]
	global_atomic_add_f32 v[34:35], v32, off
.LBB0_208:
	s_or_b64 exec, exec, s[44:45]
	v_add_u32_e32 v32, 0xa0, v142
	s_waitcnt lgkmcnt(0)
	v_ashrrev_i32_e32 v33, 31, v32
	v_lshlrev_b64 v[34:35], 11, v[32:33]
	v_lshl_add_u64 v[34:35], s[38:39], 0, v[34:35]
	v_lshl_add_u64 v[34:35], s[40:41], 1, v[34:35]
	v_lshl_add_u64 v[34:35], v[34:35], 0, v[80:81]
	v_lshl_add_u64 v[42:43], v[34:35], 0, v[114:115]
	s_waitcnt vmcnt(14)
	v_lshlrev_b32_e32 v44, 16, v228
	v_and_b32_e32 v45, 0xffff0000, v228
	v_pk_fma_f32 v[28:29], v[28:29], 0.5, v[44:45] op_sel_hi:[1,0,1]
	v_lshlrev_b32_e32 v34, 16, v229
	v_and_b32_e32 v35, 0xffff0000, v229
	v_lshlrev_b32_e32 v46, 16, v230
	v_and_b32_e32 v47, 0xffff0000, v230
	v_lshlrev_b32_e32 v36, 16, v231
	v_and_b32_e32 v37, 0xffff0000, v231
	v_mul_f32_e32 v44, v29, v29
	v_pk_fma_f32 v[30:31], v[30:31], 0.5, v[34:35] op_sel_hi:[1,0,1]
	v_pk_fma_f32 v[34:35], v[26:27], 0.5, v[36:37] op_sel_hi:[1,0,1]
	v_pk_fma_f32 v[36:37], v[24:25], 0.5, v[46:47] op_sel_hi:[1,0,1]
	v_cvt_pk_bf16_f32 v24, v28, v29
	v_cvt_pk_bf16_f32 v25, v30, v31
	v_fmac_f32_e32 v44, v28, v28
	v_cvt_pk_bf16_f32 v26, v36, v37
	v_cvt_pk_bf16_f32 v27, v34, v35
	global_store_dwordx4 v[42:43], v[24:27], off
	v_fmac_f32_e32 v44, v30, v30
	v_lshlrev_b32_e32 v28, 16, v234
	v_lshlrev_b32_e32 v24, 16, v232
	v_and_b32_e32 v25, 0xffff0000, v232
	v_lshlrev_b32_e32 v26, 16, v233
	v_and_b32_e32 v27, 0xffff0000, v233
	v_and_b32_e32 v29, 0xffff0000, v234
	v_fmac_f32_e32 v44, v31, v31
	v_lshlrev_b32_e32 v30, 16, v235
	v_and_b32_e32 v31, 0xffff0000, v235
	v_pk_fma_f32 v[22:23], v[22:23], 0.5, v[26:27] op_sel_hi:[1,0,1]
	v_pk_fma_f32 v[20:21], v[20:21], 0.5, v[24:25] op_sel_hi:[1,0,1]
	v_pk_fma_f32 v[26:27], v[16:17], 0.5, v[28:29] op_sel_hi:[1,0,1]
	v_cvt_pk_bf16_f32 v16, v20, v21
	v_pk_fma_f32 v[24:25], v[18:19], 0.5, v[30:31] op_sel_hi:[1,0,1]
	v_cvt_pk_bf16_f32 v17, v22, v23
	v_cvt_pk_bf16_f32 v18, v26, v27
	v_fmac_f32_e32 v44, v36, v36
	v_cvt_pk_bf16_f32 v19, v24, v25
	global_store_dwordx4 v[42:43], v[16:19], off offset:256
	v_fmac_f32_e32 v44, v37, v37
	v_fmac_f32_e32 v44, v34, v34
	v_mul_f32_e32 v16, v21, v21
	v_fmac_f32_e32 v16, v20, v20
	v_fmac_f32_e32 v16, v22, v22
	v_fmac_f32_e32 v16, v23, v23
	v_fmac_f32_e32 v16, v26, v26
	v_fmac_f32_e32 v16, v27, v27
	v_fmac_f32_e32 v16, v24, v24
	v_fmac_f32_e32 v44, v35, v35
	v_fmac_f32_e32 v16, v25, v25
	v_add_f32_e32 v16, v44, v16
	ds_bpermute_b32 v17, v146, v16
	s_waitcnt lgkmcnt(0)
	v_add_f32_e32 v16, v16, v17
	ds_bpermute_b32 v17, v118, v16
	s_and_saveexec_b64 s[44:45], vcc
	s_cbranch_execz .LBB0_210
	v_readlane_b32 s54, v253, 14
	v_readlane_b32 s55, v253, 15
	s_waitcnt lgkmcnt(0)
	v_add_f32_e32 v16, v16, v17
	v_lshl_add_u64 v[18:19], v[32:33], 2, s[54:55]
	global_atomic_add_f32 v[18:19], v16, off
.LBB0_210:
	s_or_b64 exec, exec, s[44:45]
	v_add_u32_e32 v16, 0xb0, v142
	s_waitcnt lgkmcnt(0)
	v_ashrrev_i32_e32 v17, 31, v16
	v_lshlrev_b64 v[18:19], 11, v[16:17]
	v_lshl_add_u64 v[18:19], s[38:39], 0, v[18:19]
	v_lshl_add_u64 v[18:19], s[40:41], 1, v[18:19]
	v_lshl_add_u64 v[18:19], v[18:19], 0, v[80:81]
	v_mov_b32_e32 v115, v81
	v_lshl_add_u64 v[26:27], v[18:19], 0, v[114:115]
	s_waitcnt vmcnt(14)
	v_lshlrev_b32_e32 v28, 16, v236
	v_and_b32_e32 v29, 0xffff0000, v236
	v_pk_fma_f32 v[12:13], v[12:13], 0.5, v[28:29] op_sel_hi:[1,0,1]
	v_lshlrev_b32_e32 v18, 16, v237
	v_and_b32_e32 v19, 0xffff0000, v237
	v_lshlrev_b32_e32 v30, 16, v238
	v_and_b32_e32 v31, 0xffff0000, v238
	v_lshlrev_b32_e32 v20, 16, v239
	v_and_b32_e32 v21, 0xffff0000, v239
	v_mul_f32_e32 v28, v13, v13
	v_pk_fma_f32 v[14:15], v[14:15], 0.5, v[18:19] op_sel_hi:[1,0,1]
	v_pk_fma_f32 v[18:19], v[10:11], 0.5, v[20:21] op_sel_hi:[1,0,1]
	v_pk_fma_f32 v[20:21], v[8:9], 0.5, v[30:31] op_sel_hi:[1,0,1]
	v_cvt_pk_bf16_f32 v8, v12, v13
	v_cvt_pk_bf16_f32 v9, v14, v15
	v_fmac_f32_e32 v28, v12, v12
	v_cvt_pk_bf16_f32 v10, v20, v21
	v_cvt_pk_bf16_f32 v11, v18, v19
	global_store_dwordx4 v[26:27], v[8:11], off
	v_fmac_f32_e32 v28, v14, v14
	v_lshlrev_b32_e32 v12, 16, v242
	v_lshlrev_b32_e32 v8, 16, v240
	v_and_b32_e32 v9, 0xffff0000, v240
	v_lshlrev_b32_e32 v10, 16, v241
	v_and_b32_e32 v11, 0xffff0000, v241
	v_and_b32_e32 v13, 0xffff0000, v242
	v_fmac_f32_e32 v28, v15, v15
	v_lshlrev_b32_e32 v14, 16, v243
	v_and_b32_e32 v15, 0xffff0000, v243
	v_pk_fma_f32 v[6:7], v[6:7], 0.5, v[10:11] op_sel_hi:[1,0,1]
	v_pk_fma_f32 v[4:5], v[4:5], 0.5, v[8:9] op_sel_hi:[1,0,1]
	v_pk_fma_f32 v[10:11], v[0:1], 0.5, v[12:13] op_sel_hi:[1,0,1]
	v_cvt_pk_bf16_f32 v0, v4, v5
	v_pk_fma_f32 v[8:9], v[2:3], 0.5, v[14:15] op_sel_hi:[1,0,1]
	v_cvt_pk_bf16_f32 v1, v6, v7
	v_cvt_pk_bf16_f32 v2, v10, v11
	v_fmac_f32_e32 v28, v20, v20
	v_cvt_pk_bf16_f32 v3, v8, v9
	global_store_dwordx4 v[26:27], v[0:3], off offset:256
	v_fmac_f32_e32 v28, v21, v21
	v_fmac_f32_e32 v28, v18, v18
	v_mul_f32_e32 v0, v5, v5
	v_fmac_f32_e32 v0, v4, v4
	v_fmac_f32_e32 v0, v6, v6
	v_fmac_f32_e32 v0, v7, v7
	v_fmac_f32_e32 v0, v10, v10
	v_fmac_f32_e32 v0, v11, v11
	v_fmac_f32_e32 v0, v8, v8
	v_fmac_f32_e32 v28, v19, v19
	v_fmac_f32_e32 v0, v9, v9
	v_add_f32_e32 v0, v28, v0
	ds_bpermute_b32 v1, v146, v0
	s_waitcnt lgkmcnt(0)
	v_add_f32_e32 v0, v0, v1
	ds_bpermute_b32 v1, v118, v0
	s_and_saveexec_b64 s[40:41], vcc
	s_cbranch_execz .LBB0_212
	v_readlane_b32 s44, v253, 14
	v_readlane_b32 s45, v253, 15
	s_waitcnt lgkmcnt(0)
	v_add_f32_e32 v0, v0, v1
	v_lshl_add_u64 v[2:3], v[16:17], 2, s[44:45]
	global_atomic_add_f32 v[2:3], v0, off

.LBB0_643:
	v_mov_b32_e32 v80, v192
	s_lshl_b32 s43, s53, 8
	s_lshl_b32 s42, s52, 8
	v_ashrrev_i32_e32 v142, 2, v80
	v_and_b32_e32 v142, 0xffffffc0, v142
	v_and_or_b32 v143, v80, 15, s43
	v_add_u32_e32 v142, v143, v142
	v_ashrrev_i32_e32 v143, 31, v142
	v_bfe_u32 v147, v80, 4, 2
	v_lshrrev_b32_e32 v80, 1, v80
	v_lshlrev_b64 v[148:149], 11, v[142:143]
	s_ashr_i32 s43, s42, 31
	v_and_b32_e32 v80, 0x60, v80
	v_lshl_add_u64 v[148:149], s[38:39], 0, v[148:149]
	v_lshl_add_u64 v[148:149], s[42:43], 1, v[148:149]
	v_lshlrev_b32_e32 v80, 1, v80
	v_lshl_add_u64 v[148:149], v[148:149], 0, v[80:81]
	v_lshlrev_b32_e32 v150, 4, v147
	v_mov_b32_e32 v151, v81
	v_lshl_add_u64 v[164:165], v[148:149], 0, v[150:151]
	global_load_dwordx4 v[148:151], v[164:165], off
	global_load_dwordx4 v[160:163], v[164:165], off offset:256
	v_mov_b32_e32 v248, v164
	v_mov_b32_e32 v249, v165
	v_add_co_u32_e32 v248, vcc, 0x8000, v248
	s_nop 1
	v_addc_co_u32_e32 v249, vcc, 0, v249, vcc
	global_load_dwordx4 v[176:179], v[248:249], off
	global_load_dwordx4 v[180:183], v[248:249], off offset:256
	v_add_co_u32_e32 v248, vcc, 0x8000, v248
	s_nop 1
	v_addc_co_u32_e32 v249, vcc, 0, v249, vcc
	global_load_dwordx4 v[184:187], v[248:249], off
	global_load_dwordx4 v[188:191], v[248:249], off offset:256
	v_add_co_u32_e32 v248, vcc, 0x8000, v248
	s_nop 1
	v_addc_co_u32_e32 v249, vcc, 0, v249, vcc
	global_load_dwordx4 v[204:207], v[248:249], off
	global_load_dwordx4 v[208:211], v[248:249], off offset:256
	v_add_co_u32_e32 v248, vcc, 0x28000, v248
	s_nop 1
	v_addc_co_u32_e32 v249, vcc, 0, v249, vcc
	global_load_dwordx4 v[212:215], v[248:249], off
	global_load_dwordx4 v[216:219], v[248:249], off offset:256
	v_add_co_u32_e32 v248, vcc, 0x8000, v248
	s_nop 1
	v_addc_co_u32_e32 v249, vcc, 0, v249, vcc
	global_load_dwordx4 v[220:223], v[248:249], off
	global_load_dwordx4 v[224:227], v[248:249], off offset:256
	v_add_co_u32_e32 v248, vcc, 0x8000, v248
	s_nop 1
	v_addc_co_u32_e32 v249, vcc, 0, v249, vcc
	global_load_dwordx4 v[228:231], v[248:249], off
	global_load_dwordx4 v[232:235], v[248:249], off offset:256
	v_add_co_u32_e32 v248, vcc, 0x8000, v248
	s_nop 1
	v_addc_co_u32_e32 v249, vcc, 0, v249, vcc
	global_load_dwordx4 v[236:239], v[248:249], off
	global_load_dwordx4 v[240:243], v[248:249], off offset:256
	v_xor_b32_e32 v146, 16, v195
	v_cmp_lt_i32_e32 vcc, v196, v197
	s_waitcnt vmcnt(14)
	v_lshlrev_b32_e32 v166, 16, v148
	v_and_b32_e32 v167, 0xffff0000, v148
	v_lshlrev_b32_e32 v170, 16, v160
	v_and_b32_e32 v171, 0xffff0000, v160
	v_lshlrev_b32_e32 v168, 16, v150
	v_and_b32_e32 v169, 0xffff0000, v150
	v_lshlrev_b32_e32 v150, 16, v151
	v_and_b32_e32 v151, 0xffff0000, v151
	v_lshlrev_b32_e32 v172, 16, v162
	v_and_b32_e32 v173, 0xffff0000, v162
	v_lshlrev_b32_e32 v162, 16, v163
	v_and_b32_e32 v163, 0xffff0000, v163
	v_pk_fma_f32 v[126:127], v[126:127], 0.5, v[166:167] op_sel_hi:[1,0,1]
	v_pk_fma_f32 v[118:119], v[118:119], 0.5, v[170:171] op_sel_hi:[1,0,1]
	v_lshlrev_b32_e32 v148, 16, v149
	v_and_b32_e32 v149, 0xffff0000, v149
	v_lshlrev_b32_e32 v160, 16, v161
	v_and_b32_e32 v161, 0xffff0000, v161
	v_pk_fma_f32 v[124:125], v[124:125], 0.5, v[150:151] op_sel_hi:[1,0,1]
	v_pk_fma_f32 v[150:151], v[116:117], 0.5, v[162:163] op_sel_hi:[1,0,1]
	v_mul_f32_e32 v116, v127, v127
	v_mul_f32_e32 v117, v119, v119
	v_pk_fma_f32 v[128:129], v[128:129], 0.5, v[148:149] op_sel_hi:[1,0,1]
	v_pk_fma_f32 v[148:149], v[120:121], 0.5, v[160:161] op_sel_hi:[1,0,1]
	v_fmac_f32_e32 v116, v126, v126
	v_fmac_f32_e32 v117, v118, v118
	v_fmac_f32_e32 v116, v128, v128
	v_fmac_f32_e32 v117, v148, v148
	v_pk_fma_f32 v[122:123], v[122:123], 0.5, v[168:169] op_sel_hi:[1,0,1]
	v_pk_fma_f32 v[160:161], v[114:115], 0.5, v[172:173] op_sel_hi:[1,0,1]
	v_fmac_f32_e32 v116, v129, v129
	v_fmac_f32_e32 v117, v149, v149
	v_fmac_f32_e32 v116, v122, v122
	v_fmac_f32_e32 v117, v160, v160
	v_fmac_f32_e32 v116, v123, v123
	v_fmac_f32_e32 v117, v161, v161
	v_cndmask_b32_e32 v174, v195, v196, vcc
	v_cmp_lt_i32_e32 vcc, v146, v197
	v_fmac_f32_e32 v116, v124, v124
	v_fmac_f32_e32 v117, v150, v150
	v_cndmask_b32_e32 v146, v195, v146, vcc
	v_fmac_f32_e32 v116, v125, v125
	v_fmac_f32_e32 v117, v151, v151
	v_lshlrev_b32_e32 v146, 2, v146
	v_add_f32_e32 v121, v116, v117
	v_cvt_pk_bf16_f32 v114, v126, v127
	ds_bpermute_b32 v126, v146, v121
	v_cvt_pk_bf16_f32 v115, v128, v129
	v_cvt_pk_bf16_f32 v116, v122, v123
	v_cvt_pk_bf16_f32 v117, v124, v125
	global_store_dwordx4 v[164:165], v[114:117], off
	v_cvt_pk_bf16_f32 v120, v118, v119
	v_lshlrev_b32_e32 v118, 2, v174
	v_cmp_eq_u32_e32 vcc, 0, v147
	s_waitcnt lgkmcnt(0)
	v_add_f32_e32 v114, v121, v126
	ds_bpermute_b32 v115, v118, v114
	v_cvt_pk_bf16_f32 v121, v148, v149
	v_cvt_pk_bf16_f32 v122, v160, v161
	v_cvt_pk_bf16_f32 v123, v150, v151
	global_store_dwordx4 v[164:165], v[120:123], off offset:256
	s_and_saveexec_b64 s[44:45], vcc
	s_cbranch_execz .LBB0_645
	v_lshl_add_u64 v[116:117], v[142:143], 2, s[26:27]
	s_waitcnt lgkmcnt(0)
	v_add_f32_e32 v114, v114, v115
	global_atomic_add_f32 v[116:117], v114, off
.LBB0_645:
	s_or_b64 exec, exec, s[44:45]
	v_or_b32_e32 v116, 16, v142
	v_ashrrev_i32_e32 v117, 31, v116
	s_waitcnt lgkmcnt(0)
	v_lshlrev_b64 v[114:115], 11, v[116:117]
	v_lshl_add_u64 v[114:115], s[38:39], 0, v[114:115]
	v_lshlrev_b32_e32 v119, 3, v147
	v_lshl_add_u64 v[114:115], s[42:43], 1, v[114:115]
	v_lshl_add_u64 v[120:121], v[114:115], 0, v[80:81]
	v_lshlrev_b32_e32 v114, 1, v119
	v_mov_b32_e32 v115, v81
	v_lshl_add_u64 v[128:129], v[120:121], 0, v[114:115]
	s_waitcnt vmcnt(14)
	v_lshlrev_b32_e32 v148, 16, v176
	v_and_b32_e32 v149, 0xffff0000, v176
	v_pk_fma_f32 v[110:111], v[110:111], 0.5, v[148:149] op_sel_hi:[1,0,1]
	v_lshlrev_b32_e32 v120, 16, v177
	v_and_b32_e32 v121, 0xffff0000, v177
	v_lshlrev_b32_e32 v150, 16, v178
	v_and_b32_e32 v151, 0xffff0000, v178
	v_lshlrev_b32_e32 v122, 16, v179
	v_and_b32_e32 v123, 0xffff0000, v179
	v_mul_f32_e32 v119, v111, v111
	v_pk_fma_f32 v[112:113], v[112:113], 0.5, v[120:121] op_sel_hi:[1,0,1]
	v_pk_fma_f32 v[120:121], v[108:109], 0.5, v[122:123] op_sel_hi:[1,0,1]
	v_pk_fma_f32 v[122:123], v[106:107], 0.5, v[150:151] op_sel_hi:[1,0,1]
	v_cvt_pk_bf16_f32 v106, v110, v111
	v_cvt_pk_bf16_f32 v107, v112, v113
	v_fmac_f32_e32 v119, v110, v110
	v_cvt_pk_bf16_f32 v108, v122, v123
	v_cvt_pk_bf16_f32 v109, v120, v121
	global_store_dwordx4 v[128:129], v[106:109], off
	v_fmac_f32_e32 v119, v112, v112
	v_lshlrev_b32_e32 v110, 16, v182
	v_lshlrev_b32_e32 v106, 16, v180
	v_and_b32_e32 v107, 0xffff0000, v180
	v_lshlrev_b32_e32 v108, 16, v181
	v_and_b32_e32 v109, 0xffff0000, v181
	v_and_b32_e32 v111, 0xffff0000, v182
	v_fmac_f32_e32 v119, v113, v113
	v_lshlrev_b32_e32 v112, 16, v183
	v_and_b32_e32 v113, 0xffff0000, v183
	v_pk_fma_f32 v[104:105], v[104:105], 0.5, v[108:109] op_sel_hi:[1,0,1]
	v_pk_fma_f32 v[102:103], v[102:103], 0.5, v[106:107] op_sel_hi:[1,0,1]
	v_pk_fma_f32 v[108:109], v[98:99], 0.5, v[110:111] op_sel_hi:[1,0,1]
	v_cvt_pk_bf16_f32 v98, v102, v103
	v_pk_fma_f32 v[106:107], v[100:101], 0.5, v[112:113] op_sel_hi:[1,0,1]
	v_cvt_pk_bf16_f32 v99, v104, v105
	v_cvt_pk_bf16_f32 v100, v108, v109
	v_fmac_f32_e32 v119, v122, v122
	v_cvt_pk_bf16_f32 v101, v106, v107
	global_store_dwordx4 v[128:129], v[98:101], off offset:256
	v_fmac_f32_e32 v119, v123, v123
	v_fmac_f32_e32 v119, v120, v120
	v_mul_f32_e32 v98, v103, v103
	v_fmac_f32_e32 v98, v102, v102
	v_fmac_f32_e32 v98, v104, v104
	v_fmac_f32_e32 v98, v105, v105
	v_fmac_f32_e32 v98, v108, v108
	v_fmac_f32_e32 v98, v109, v109
	v_fmac_f32_e32 v98, v106, v106
	v_fmac_f32_e32 v119, v121, v121
	v_fmac_f32_e32 v98, v107, v107
	v_add_f32_e32 v98, v119, v98
	ds_bpermute_b32 v99, v146, v98
	s_waitcnt lgkmcnt(0)
	v_add_f32_e32 v98, v98, v99
	ds_bpermute_b32 v99, v118, v98
	s_and_saveexec_b64 s[44:45], vcc
	s_cbranch_execz .LBB0_647
	v_lshl_add_u64 v[100:101], v[116:117], 2, s[26:27]
	s_waitcnt lgkmcnt(0)
	v_add_f32_e32 v98, v98, v99
	global_atomic_add_f32 v[100:101], v98, off
.LBB0_647:
	s_or_b64 exec, exec, s[44:45]
	v_or_b32_e32 v98, 32, v142
	s_waitcnt lgkmcnt(0)
	v_ashrrev_i32_e32 v99, 31, v98
	v_lshlrev_b64 v[100:101], 11, v[98:99]
	v_lshl_add_u64 v[100:101], s[38:39], 0, v[100:101]
	v_lshl_add_u64 v[100:101], s[42:43], 1, v[100:101]
	v_lshl_add_u64 v[100:101], v[100:101], 0, v[80:81]
	v_lshl_add_u64 v[108:109], v[100:101], 0, v[114:115]
	s_waitcnt vmcnt(14)
	v_lshlrev_b32_e32 v110, 16, v184
	v_and_b32_e32 v111, 0xffff0000, v184
	v_pk_fma_f32 v[94:95], v[94:95], 0.5, v[110:111] op_sel_hi:[1,0,1]
	v_lshlrev_b32_e32 v100, 16, v185
	v_and_b32_e32 v101, 0xffff0000, v185
	v_lshlrev_b32_e32 v112, 16, v186
	v_and_b32_e32 v113, 0xffff0000, v186
	v_lshlrev_b32_e32 v102, 16, v187
	v_and_b32_e32 v103, 0xffff0000, v187
	v_mul_f32_e32 v110, v95, v95
	v_pk_fma_f32 v[96:97], v[96:97], 0.5, v[100:101] op_sel_hi:[1,0,1]
	v_pk_fma_f32 v[100:101], v[92:93], 0.5, v[102:103] op_sel_hi:[1,0,1]
	v_pk_fma_f32 v[102:103], v[90:91], 0.5, v[112:113] op_sel_hi:[1,0,1]
	v_cvt_pk_bf16_f32 v90, v94, v95
	v_cvt_pk_bf16_f32 v91, v96, v97
	v_fmac_f32_e32 v110, v94, v94
	v_cvt_pk_bf16_f32 v92, v102, v103
	v_cvt_pk_bf16_f32 v93, v100, v101
	global_store_dwordx4 v[108:109], v[90:93], off
	v_fmac_f32_e32 v110, v96, v96
	v_lshlrev_b32_e32 v94, 16, v190
	v_lshlrev_b32_e32 v90, 16, v188
	v_and_b32_e32 v91, 0xffff0000, v188
	v_lshlrev_b32_e32 v92, 16, v189
	v_and_b32_e32 v93, 0xffff0000, v189
	v_and_b32_e32 v95, 0xffff0000, v190
	v_fmac_f32_e32 v110, v97, v97
	v_lshlrev_b32_e32 v96, 16, v191
	v_and_b32_e32 v97, 0xffff0000, v191
	v_pk_fma_f32 v[88:89], v[88:89], 0.5, v[92:93] op_sel_hi:[1,0,1]
	v_pk_fma_f32 v[86:87], v[86:87], 0.5, v[90:91] op_sel_hi:[1,0,1]
	v_pk_fma_f32 v[92:93], v[82:83], 0.5, v[94:95] op_sel_hi:[1,0,1]
	v_cvt_pk_bf16_f32 v82, v86, v87
	v_pk_fma_f32 v[90:91], v[84:85], 0.5, v[96:97] op_sel_hi:[1,0,1]
	v_cvt_pk_bf16_f32 v83, v88, v89
	v_cvt_pk_bf16_f32 v84, v92, v93
	v_fmac_f32_e32 v110, v102, v102
	v_cvt_pk_bf16_f32 v85, v90, v91
	global_store_dwordx4 v[108:109], v[82:85], off offset:256
	v_fmac_f32_e32 v110, v103, v103
	v_fmac_f32_e32 v110, v100, v100
	v_mul_f32_e32 v82, v87, v87
	v_fmac_f32_e32 v82, v86, v86
	v_fmac_f32_e32 v82, v88, v88
	v_fmac_f32_e32 v82, v89, v89
	v_fmac_f32_e32 v82, v92, v92
	v_fmac_f32_e32 v82, v93, v93
	v_fmac_f32_e32 v82, v90, v90
	v_fmac_f32_e32 v110, v101, v101
	v_fmac_f32_e32 v82, v91, v91
	v_add_f32_e32 v82, v110, v82
	ds_bpermute_b32 v83, v146, v82
	s_waitcnt lgkmcnt(0)
	v_add_f32_e32 v82, v82, v83
	ds_bpermute_b32 v83, v118, v82
	s_and_saveexec_b64 s[44:45], vcc
	s_cbranch_execz .LBB0_649
	v_lshl_add_u64 v[84:85], v[98:99], 2, s[26:27]
	s_waitcnt lgkmcnt(0)
	v_add_f32_e32 v82, v82, v83
	global_atomic_add_f32 v[84:85], v82, off
.LBB0_649:
	s_or_b64 exec, exec, s[44:45]
	v_or_b32_e32 v82, 48, v142
	s_waitcnt lgkmcnt(0)
	v_ashrrev_i32_e32 v83, 31, v82
	v_lshlrev_b64 v[84:85], 11, v[82:83]
	v_lshl_add_u64 v[84:85], s[38:39], 0, v[84:85]
	v_lshl_add_u64 v[84:85], s[42:43], 1, v[84:85]
	v_lshl_add_u64 v[84:85], v[84:85], 0, v[80:81]
	v_mov_b32_e32 v115, v81
	v_lshl_add_u64 v[92:93], v[84:85], 0, v[114:115]
	s_waitcnt vmcnt(14)
	v_lshlrev_b32_e32 v94, 16, v204
	v_and_b32_e32 v95, 0xffff0000, v204
	v_pk_fma_f32 v[76:77], v[76:77], 0.5, v[94:95] op_sel_hi:[1,0,1]
	v_lshlrev_b32_e32 v84, 16, v205
	v_and_b32_e32 v85, 0xffff0000, v205
	v_lshlrev_b32_e32 v96, 16, v206
	v_and_b32_e32 v97, 0xffff0000, v206
	v_lshlrev_b32_e32 v86, 16, v207
	v_and_b32_e32 v87, 0xffff0000, v207
	v_mul_f32_e32 v94, v77, v77
	v_pk_fma_f32 v[78:79], v[78:79], 0.5, v[84:85] op_sel_hi:[1,0,1]
	v_pk_fma_f32 v[84:85], v[74:75], 0.5, v[86:87] op_sel_hi:[1,0,1]
	v_pk_fma_f32 v[86:87], v[72:73], 0.5, v[96:97] op_sel_hi:[1,0,1]
	v_cvt_pk_bf16_f32 v72, v76, v77
	v_cvt_pk_bf16_f32 v73, v78, v79
	v_fmac_f32_e32 v94, v76, v76
	v_cvt_pk_bf16_f32 v74, v86, v87
	v_cvt_pk_bf16_f32 v75, v84, v85
	global_store_dwordx4 v[92:93], v[72:75], off
	v_fmac_f32_e32 v94, v78, v78
	v_lshlrev_b32_e32 v76, 16, v210
	v_lshlrev_b32_e32 v72, 16, v208
	v_and_b32_e32 v73, 0xffff0000, v208
	v_lshlrev_b32_e32 v74, 16, v209
	v_and_b32_e32 v75, 0xffff0000, v209
	v_and_b32_e32 v77, 0xffff0000, v210
	v_fmac_f32_e32 v94, v79, v79
	v_lshlrev_b32_e32 v78, 16, v211
	v_and_b32_e32 v79, 0xffff0000, v211
	v_pk_fma_f32 v[70:71], v[70:71], 0.5, v[74:75] op_sel_hi:[1,0,1]
	v_pk_fma_f32 v[68:69], v[68:69], 0.5, v[72:73] op_sel_hi:[1,0,1]
	v_pk_fma_f32 v[74:75], v[64:65], 0.5, v[76:77] op_sel_hi:[1,0,1]
	v_cvt_pk_bf16_f32 v64, v68, v69
	v_pk_fma_f32 v[72:73], v[66:67], 0.5, v[78:79] op_sel_hi:[1,0,1]
	v_cvt_pk_bf16_f32 v65, v70, v71
	v_cvt_pk_bf16_f32 v66, v74, v75
	v_fmac_f32_e32 v94, v86, v86
	v_cvt_pk_bf16_f32 v67, v72, v73
	global_store_dwordx4 v[92:93], v[64:67], off offset:256
	v_fmac_f32_e32 v94, v87, v87
	v_fmac_f32_e32 v94, v84, v84
	v_mul_f32_e32 v64, v69, v69
	v_fmac_f32_e32 v64, v68, v68
	v_fmac_f32_e32 v64, v70, v70
	v_fmac_f32_e32 v64, v71, v71
	v_fmac_f32_e32 v64, v74, v74
	v_fmac_f32_e32 v64, v75, v75
	v_fmac_f32_e32 v64, v72, v72
	v_fmac_f32_e32 v94, v85, v85
	v_fmac_f32_e32 v64, v73, v73
	v_add_f32_e32 v64, v94, v64
	ds_bpermute_b32 v65, v146, v64
	s_waitcnt lgkmcnt(0)
	v_add_f32_e32 v64, v64, v65
	ds_bpermute_b32 v65, v118, v64
	s_and_saveexec_b64 s[44:45], vcc
	s_cbranch_execz .LBB0_651
	v_lshl_add_u64 v[66:67], v[82:83], 2, s[26:27]
	s_waitcnt lgkmcnt(0)
	v_add_f32_e32 v64, v64, v65
	global_atomic_add_f32 v[66:67], v64, off
.LBB0_651:
	s_or_b64 exec, exec, s[44:45]
	v_add_u32_e32 v64, 0x80, v142
	s_waitcnt lgkmcnt(0)
	v_ashrrev_i32_e32 v65, 31, v64
	v_lshlrev_b64 v[66:67], 11, v[64:65]
	v_lshl_add_u64 v[66:67], s[38:39], 0, v[66:67]
	v_lshl_add_u64 v[66:67], s[42:43], 1, v[66:67]
	v_lshl_add_u64 v[66:67], v[66:67], 0, v[80:81]
	v_lshl_add_u64 v[74:75], v[66:67], 0, v[114:115]
	s_waitcnt vmcnt(14)
	v_lshlrev_b32_e32 v76, 16, v212
	v_and_b32_e32 v77, 0xffff0000, v212
	v_pk_fma_f32 v[60:61], v[60:61], 0.5, v[76:77] op_sel_hi:[1,0,1]
	v_lshlrev_b32_e32 v66, 16, v213
	v_and_b32_e32 v67, 0xffff0000, v213
	v_lshlrev_b32_e32 v78, 16, v214
	v_and_b32_e32 v79, 0xffff0000, v214
	v_lshlrev_b32_e32 v68, 16, v215
	v_and_b32_e32 v69, 0xffff0000, v215
	v_mul_f32_e32 v76, v61, v61
	v_pk_fma_f32 v[62:63], v[62:63], 0.5, v[66:67] op_sel_hi:[1,0,1]
	v_pk_fma_f32 v[66:67], v[58:59], 0.5, v[68:69] op_sel_hi:[1,0,1]
	v_pk_fma_f32 v[68:69], v[56:57], 0.5, v[78:79] op_sel_hi:[1,0,1]
	v_cvt_pk_bf16_f32 v56, v60, v61
	v_cvt_pk_bf16_f32 v57, v62, v63
	v_fmac_f32_e32 v76, v60, v60
	v_cvt_pk_bf16_f32 v58, v68, v69
	v_cvt_pk_bf16_f32 v59, v66, v67
	global_store_dwordx4 v[74:75], v[56:59], off
	v_fmac_f32_e32 v76, v62, v62
	v_lshlrev_b32_e32 v60, 16, v218
	v_lshlrev_b32_e32 v56, 16, v216
	v_and_b32_e32 v57, 0xffff0000, v216
	v_lshlrev_b32_e32 v58, 16, v217
	v_and_b32_e32 v59, 0xffff0000, v217
	v_and_b32_e32 v61, 0xffff0000, v218
	v_fmac_f32_e32 v76, v63, v63
	v_lshlrev_b32_e32 v62, 16, v219
	v_and_b32_e32 v63, 0xffff0000, v219
	v_pk_fma_f32 v[54:55], v[54:55], 0.5, v[58:59] op_sel_hi:[1,0,1]
	v_pk_fma_f32 v[52:53], v[52:53], 0.5, v[56:57] op_sel_hi:[1,0,1]
	v_pk_fma_f32 v[58:59], v[48:49], 0.5, v[60:61] op_sel_hi:[1,0,1]
	v_cvt_pk_bf16_f32 v48, v52, v53
	v_pk_fma_f32 v[56:57], v[50:51], 0.5, v[62:63] op_sel_hi:[1,0,1]
	v_cvt_pk_bf16_f32 v49, v54, v55
	v_cvt_pk_bf16_f32 v50, v58, v59
	v_fmac_f32_e32 v76, v68, v68
	v_cvt_pk_bf16_f32 v51, v56, v57
	global_store_dwordx4 v[74:75], v[48:51], off offset:256
	v_fmac_f32_e32 v76, v69, v69
	v_fmac_f32_e32 v76, v66, v66
	v_mul_f32_e32 v48, v53, v53
	v_fmac_f32_e32 v48, v52, v52
	v_fmac_f32_e32 v48, v54, v54
	v_fmac_f32_e32 v48, v55, v55
	v_fmac_f32_e32 v48, v58, v58
	v_fmac_f32_e32 v48, v59, v59
	v_fmac_f32_e32 v48, v56, v56
	v_fmac_f32_e32 v76, v67, v67
	v_fmac_f32_e32 v48, v57, v57
	v_add_f32_e32 v48, v76, v48
	ds_bpermute_b32 v49, v146, v48
	s_waitcnt lgkmcnt(0)
	v_add_f32_e32 v48, v48, v49
	ds_bpermute_b32 v49, v118, v48
	s_and_saveexec_b64 s[44:45], vcc
	s_cbranch_execz .LBB0_653
	v_lshl_add_u64 v[50:51], v[64:65], 2, s[26:27]
	s_waitcnt lgkmcnt(0)
	v_add_f32_e32 v48, v48, v49
	global_atomic_add_f32 v[50:51], v48, off
.LBB0_653:
	s_or_b64 exec, exec, s[44:45]
	v_add_u32_e32 v48, 0x90, v142
	s_waitcnt lgkmcnt(0)
	v_ashrrev_i32_e32 v49, 31, v48
	v_lshlrev_b64 v[50:51], 11, v[48:49]
	v_lshl_add_u64 v[50:51], s[38:39], 0, v[50:51]
	v_lshl_add_u64 v[50:51], s[42:43], 1, v[50:51]
	v_lshl_add_u64 v[50:51], v[50:51], 0, v[80:81]
	v_mov_b32_e32 v115, v81
	v_lshl_add_u64 v[58:59], v[50:51], 0, v[114:115]
	s_waitcnt vmcnt(14)
	v_lshlrev_b32_e32 v60, 16, v220
	v_and_b32_e32 v61, 0xffff0000, v220
	v_pk_fma_f32 v[44:45], v[44:45], 0.5, v[60:61] op_sel_hi:[1,0,1]
	v_lshlrev_b32_e32 v50, 16, v221
	v_and_b32_e32 v51, 0xffff0000, v221
	v_lshlrev_b32_e32 v62, 16, v222
	v_and_b32_e32 v63, 0xffff0000, v222
	v_lshlrev_b32_e32 v52, 16, v223
	v_and_b32_e32 v53, 0xffff0000, v223
	v_mul_f32_e32 v60, v45, v45
	v_pk_fma_f32 v[46:47], v[46:47], 0.5, v[50:51] op_sel_hi:[1,0,1]
	v_pk_fma_f32 v[50:51], v[42:43], 0.5, v[52:53] op_sel_hi:[1,0,1]
	v_pk_fma_f32 v[52:53], v[40:41], 0.5, v[62:63] op_sel_hi:[1,0,1]
	v_cvt_pk_bf16_f32 v40, v44, v45
	v_cvt_pk_bf16_f32 v41, v46, v47
	v_fmac_f32_e32 v60, v44, v44
	v_cvt_pk_bf16_f32 v42, v52, v53
	v_cvt_pk_bf16_f32 v43, v50, v51
	global_store_dwordx4 v[58:59], v[40:43], off
	v_fmac_f32_e32 v60, v46, v46
	v_lshlrev_b32_e32 v44, 16, v226
	v_lshlrev_b32_e32 v40, 16, v224
	v_and_b32_e32 v41, 0xffff0000, v224
	v_lshlrev_b32_e32 v42, 16, v225
	v_and_b32_e32 v43, 0xffff0000, v225
	v_and_b32_e32 v45, 0xffff0000, v226
	v_fmac_f32_e32 v60, v47, v47
	v_lshlrev_b32_e32 v46, 16, v227
	v_and_b32_e32 v47, 0xffff0000, v227
	v_pk_fma_f32 v[38:39], v[38:39], 0.5, v[42:43] op_sel_hi:[1,0,1]
	v_pk_fma_f32 v[36:37], v[36:37], 0.5, v[40:41] op_sel_hi:[1,0,1]
	v_pk_fma_f32 v[42:43], v[32:33], 0.5, v[44:45] op_sel_hi:[1,0,1]
	v_cvt_pk_bf16_f32 v32, v36, v37
	v_pk_fma_f32 v[40:41], v[34:35], 0.5, v[46:47] op_sel_hi:[1,0,1]
	v_cvt_pk_bf16_f32 v33, v38, v39
	v_cvt_pk_bf16_f32 v34, v42, v43
	v_fmac_f32_e32 v60, v52, v52
	v_cvt_pk_bf16_f32 v35, v40, v41
	global_store_dwordx4 v[58:59], v[32:35], off offset:256
	v_fmac_f32_e32 v60, v53, v53
	v_fmac_f32_e32 v60, v50, v50
	v_mul_f32_e32 v32, v37, v37
	v_fmac_f32_e32 v32, v36, v36
	v_fmac_f32_e32 v32, v38, v38
	v_fmac_f32_e32 v32, v39, v39
	v_fmac_f32_e32 v32, v42, v42
	v_fmac_f32_e32 v32, v43, v43
	v_fmac_f32_e32 v32, v40, v40
	v_fmac_f32_e32 v60, v51, v51
	v_fmac_f32_e32 v32, v41, v41
	v_add_f32_e32 v32, v60, v32
	ds_bpermute_b32 v33, v146, v32
	s_waitcnt lgkmcnt(0)
	v_add_f32_e32 v32, v32, v33
	ds_bpermute_b32 v33, v118, v32
	s_and_saveexec_b64 s[44:45], vcc
	s_cbranch_execz .LBB0_655
	v_lshl_add_u64 v[34:35], v[48:49], 2, s[26:27]
	s_waitcnt lgkmcnt(0)
	v_add_f32_e32 v32, v32, v33
	global_atomic_add_f32 v[34:35], v32, off
.LBB0_655:
	s_or_b64 exec, exec, s[44:45]
	v_add_u32_e32 v32, 0xa0, v142
	s_waitcnt lgkmcnt(0)
	v_ashrrev_i32_e32 v33, 31, v32
	v_lshlrev_b64 v[34:35], 11, v[32:33]
	v_lshl_add_u64 v[34:35], s[38:39], 0, v[34:35]
	v_lshl_add_u64 v[34:35], s[42:43], 1, v[34:35]
	v_lshl_add_u64 v[34:35], v[34:35], 0, v[80:81]
	v_lshl_add_u64 v[42:43], v[34:35], 0, v[114:115]
	s_waitcnt vmcnt(14)
	v_lshlrev_b32_e32 v44, 16, v228
	v_and_b32_e32 v45, 0xffff0000, v228
	v_pk_fma_f32 v[28:29], v[28:29], 0.5, v[44:45] op_sel_hi:[1,0,1]
	v_lshlrev_b32_e32 v34, 16, v229
	v_and_b32_e32 v35, 0xffff0000, v229
	v_lshlrev_b32_e32 v46, 16, v230
	v_and_b32_e32 v47, 0xffff0000, v230
	v_lshlrev_b32_e32 v36, 16, v231
	v_and_b32_e32 v37, 0xffff0000, v231
	v_mul_f32_e32 v44, v29, v29
	v_pk_fma_f32 v[30:31], v[30:31], 0.5, v[34:35] op_sel_hi:[1,0,1]
	v_pk_fma_f32 v[34:35], v[26:27], 0.5, v[36:37] op_sel_hi:[1,0,1]
	v_pk_fma_f32 v[36:37], v[24:25], 0.5, v[46:47] op_sel_hi:[1,0,1]
	v_cvt_pk_bf16_f32 v24, v28, v29
	v_cvt_pk_bf16_f32 v25, v30, v31
	v_fmac_f32_e32 v44, v28, v28
	v_cvt_pk_bf16_f32 v26, v36, v37
	v_cvt_pk_bf16_f32 v27, v34, v35
	global_store_dwordx4 v[42:43], v[24:27], off
	v_fmac_f32_e32 v44, v30, v30
	v_lshlrev_b32_e32 v28, 16, v234
	v_lshlrev_b32_e32 v24, 16, v232
	v_and_b32_e32 v25, 0xffff0000, v232
	v_lshlrev_b32_e32 v26, 16, v233
	v_and_b32_e32 v27, 0xffff0000, v233
	v_and_b32_e32 v29, 0xffff0000, v234
	v_fmac_f32_e32 v44, v31, v31
	v_lshlrev_b32_e32 v30, 16, v235
	v_and_b32_e32 v31, 0xffff0000, v235
	v_pk_fma_f32 v[22:23], v[22:23], 0.5, v[26:27] op_sel_hi:[1,0,1]
	v_pk_fma_f32 v[20:21], v[20:21], 0.5, v[24:25] op_sel_hi:[1,0,1]
	v_pk_fma_f32 v[26:27], v[16:17], 0.5, v[28:29] op_sel_hi:[1,0,1]
	v_cvt_pk_bf16_f32 v16, v20, v21
	v_pk_fma_f32 v[24:25], v[18:19], 0.5, v[30:31] op_sel_hi:[1,0,1]
	v_cvt_pk_bf16_f32 v17, v22, v23
	v_cvt_pk_bf16_f32 v18, v26, v27
	v_fmac_f32_e32 v44, v36, v36
	v_cvt_pk_bf16_f32 v19, v24, v25
	global_store_dwordx4 v[42:43], v[16:19], off offset:256
	v_fmac_f32_e32 v44, v37, v37
	v_fmac_f32_e32 v44, v34, v34
	v_mul_f32_e32 v16, v21, v21
	v_fmac_f32_e32 v16, v20, v20
	v_fmac_f32_e32 v16, v22, v22
	v_fmac_f32_e32 v16, v23, v23
	v_fmac_f32_e32 v16, v26, v26
	v_fmac_f32_e32 v16, v27, v27
	v_fmac_f32_e32 v16, v24, v24
	v_fmac_f32_e32 v44, v35, v35
	v_fmac_f32_e32 v16, v25, v25
	v_add_f32_e32 v16, v44, v16
	ds_bpermute_b32 v17, v146, v16
	s_waitcnt lgkmcnt(0)
	v_add_f32_e32 v16, v16, v17
	ds_bpermute_b32 v17, v118, v16
	s_and_saveexec_b64 s[44:45], vcc
	s_cbranch_execz .LBB0_657
	v_lshl_add_u64 v[18:19], v[32:33], 2, s[26:27]
	s_waitcnt lgkmcnt(0)
	v_add_f32_e32 v16, v16, v17
	global_atomic_add_f32 v[18:19], v16, off
.LBB0_657:
	s_or_b64 exec, exec, s[44:45]
	v_add_u32_e32 v16, 0xb0, v142
	s_waitcnt lgkmcnt(0)
	v_ashrrev_i32_e32 v17, 31, v16
	v_lshlrev_b64 v[18:19], 11, v[16:17]
	v_lshl_add_u64 v[18:19], s[38:39], 0, v[18:19]
	v_lshl_add_u64 v[18:19], s[42:43], 1, v[18:19]
	v_lshl_add_u64 v[18:19], v[18:19], 0, v[80:81]
	v_mov_b32_e32 v115, v81
	v_lshl_add_u64 v[26:27], v[18:19], 0, v[114:115]
	s_waitcnt vmcnt(14)
	v_lshlrev_b32_e32 v28, 16, v236
	v_and_b32_e32 v29, 0xffff0000, v236
	v_pk_fma_f32 v[12:13], v[12:13], 0.5, v[28:29] op_sel_hi:[1,0,1]
	v_lshlrev_b32_e32 v18, 16, v237
	v_and_b32_e32 v19, 0xffff0000, v237
	v_lshlrev_b32_e32 v30, 16, v238
	v_and_b32_e32 v31, 0xffff0000, v238
	v_lshlrev_b32_e32 v20, 16, v239
	v_and_b32_e32 v21, 0xffff0000, v239
	v_mul_f32_e32 v28, v13, v13
	v_pk_fma_f32 v[14:15], v[14:15], 0.5, v[18:19] op_sel_hi:[1,0,1]
	v_pk_fma_f32 v[18:19], v[10:11], 0.5, v[20:21] op_sel_hi:[1,0,1]
	v_pk_fma_f32 v[20:21], v[8:9], 0.5, v[30:31] op_sel_hi:[1,0,1]
	v_cvt_pk_bf16_f32 v8, v12, v13
	v_cvt_pk_bf16_f32 v9, v14, v15
	v_fmac_f32_e32 v28, v12, v12
	v_cvt_pk_bf16_f32 v10, v20, v21
	v_cvt_pk_bf16_f32 v11, v18, v19
	global_store_dwordx4 v[26:27], v[8:11], off
	v_fmac_f32_e32 v28, v14, v14
	v_lshlrev_b32_e32 v12, 16, v242
	v_lshlrev_b32_e32 v8, 16, v240
	v_and_b32_e32 v9, 0xffff0000, v240
	v_lshlrev_b32_e32 v10, 16, v241
	v_and_b32_e32 v11, 0xffff0000, v241
	v_and_b32_e32 v13, 0xffff0000, v242
	v_fmac_f32_e32 v28, v15, v15
	v_lshlrev_b32_e32 v14, 16, v243
	v_and_b32_e32 v15, 0xffff0000, v243
	v_pk_fma_f32 v[6:7], v[6:7], 0.5, v[10:11] op_sel_hi:[1,0,1]
	v_pk_fma_f32 v[4:5], v[4:5], 0.5, v[8:9] op_sel_hi:[1,0,1]
	v_pk_fma_f32 v[10:11], v[0:1], 0.5, v[12:13] op_sel_hi:[1,0,1]
	v_cvt_pk_bf16_f32 v0, v4, v5
	v_pk_fma_f32 v[8:9], v[2:3], 0.5, v[14:15] op_sel_hi:[1,0,1]
	v_cvt_pk_bf16_f32 v1, v6, v7
	v_cvt_pk_bf16_f32 v2, v10, v11
	v_fmac_f32_e32 v28, v20, v20
	v_cvt_pk_bf16_f32 v3, v8, v9
	global_store_dwordx4 v[26:27], v[0:3], off offset:256
	v_fmac_f32_e32 v28, v21, v21
	v_fmac_f32_e32 v28, v18, v18
	v_mul_f32_e32 v0, v5, v5
	v_fmac_f32_e32 v0, v4, v4
	v_fmac_f32_e32 v0, v6, v6
	v_fmac_f32_e32 v0, v7, v7
	v_fmac_f32_e32 v0, v10, v10
	v_fmac_f32_e32 v0, v11, v11
	v_fmac_f32_e32 v0, v8, v8
	v_fmac_f32_e32 v28, v19, v19
	v_fmac_f32_e32 v0, v9, v9
	v_add_f32_e32 v0, v28, v0
	ds_bpermute_b32 v1, v146, v0
	s_waitcnt lgkmcnt(0)
	v_add_f32_e32 v0, v0, v1
	ds_bpermute_b32 v1, v118, v0
	s_and_saveexec_b64 s[42:43], vcc
	s_cbranch_execz .LBB0_659
	v_lshl_add_u64 v[2:3], v[16:17], 2, s[26:27]
	s_waitcnt lgkmcnt(0)
	v_add_f32_e32 v0, v0, v1
	global_atomic_add_f32 v[2:3], v0, off
